# also the attention item epilogue: 16 serialised z-gate loads issued together, each landing in its own unpack destination
# baseline (speedup 1.0000x reference)
.LBB0_83:
	ds_bpermute_b32 v0, v176, v69
	s_waitcnt lgkmcnt(0)
	v_add_f32_e32 v0, v69, v0
	v_div_scale_f32 v1, s[2:3], v0, v0, 1.0
	v_rcp_f32_e32 v2, v1
	s_nop 0
	v_fma_f32 v68, -v1, v2, 1.0
	v_fmac_f32_e32 v2, v68, v2
	v_div_scale_f32 v68, vcc, 1.0, v0, 1.0
	v_mul_f32_e32 v69, v68, v2
	v_fma_f32 v70, -v1, v69, v68
	v_fmac_f32_e32 v69, v70, v2
	v_fma_f32 v1, -v1, v69, v68
	v_div_fmas_f32 v1, v1, v2, v69
	v_div_fixup_f32 v0, v1, v0, 1.0
	v_mul_f32_e32 v72, v159, v0
	global_load_dwordx2 v[136:137], v[144:145], off
	global_load_dwordx2 v[76:77], v[144:145], off offset:16
	global_load_dwordx2 v[80:81], v[144:145], off offset:32
	global_load_dwordx2 v[84:85], v[144:145], off offset:48
	global_load_dwordx2 v[88:89], v[144:145], off offset:64
	global_load_dwordx2 v[92:93], v[144:145], off offset:80
	global_load_dwordx2 v[96:97], v[144:145], off offset:96
	global_load_dwordx2 v[100:101], v[144:145], off offset:112
	global_load_dwordx2 v[104:105], v[144:145], off offset:128
	global_load_dwordx2 v[108:109], v[144:145], off offset:144
	global_load_dwordx2 v[116:117], v[144:145], off offset:160
	global_load_dwordx2 v[120:121], v[144:145], off offset:176
	global_load_dwordx2 v[124:125], v[144:145], off offset:192
	global_load_dwordx2 v[128:129], v[144:145], off offset:208
	global_load_dwordx2 v[132:133], v[144:145], off offset:224
	global_load_dwordx2 v[0:1], v[144:145], off offset:240
	v_lshlrev_b32_e32 v2, 1, v146
	v_lshl_add_u64 v[70:71], v[148:149], 0, v[2:3]
	s_waitcnt vmcnt(0)
	v_lshlrev_b32_e32 v134, 16, v136
	v_and_b32_e32 v135, 0xffff0000, v136
	v_lshlrev_b32_e32 v136, 16, v137
	v_and_b32_e32 v137, 0xffff0000, v137
	v_lshlrev_b32_e32 v74, 16, v76
	v_and_b32_e32 v75, 0xffff0000, v76
	v_lshlrev_b32_e32 v76, 16, v77
	v_and_b32_e32 v77, 0xffff0000, v77
	v_lshlrev_b32_e32 v78, 16, v80
	v_and_b32_e32 v79, 0xffff0000, v80
	v_lshlrev_b32_e32 v80, 16, v81
	v_and_b32_e32 v81, 0xffff0000, v81
	v_lshlrev_b32_e32 v82, 16, v84
	v_and_b32_e32 v83, 0xffff0000, v84
	v_lshlrev_b32_e32 v84, 16, v85
	v_and_b32_e32 v85, 0xffff0000, v85
	v_lshlrev_b32_e32 v86, 16, v88
	v_and_b32_e32 v87, 0xffff0000, v88
	v_lshlrev_b32_e32 v88, 16, v89
	v_and_b32_e32 v89, 0xffff0000, v89
	v_lshlrev_b32_e32 v90, 16, v92
	v_and_b32_e32 v91, 0xffff0000, v92
	v_lshlrev_b32_e32 v92, 16, v93
	v_and_b32_e32 v93, 0xffff0000, v93
	v_lshlrev_b32_e32 v94, 16, v96
	v_and_b32_e32 v95, 0xffff0000, v96
	v_lshlrev_b32_e32 v96, 16, v97
	v_and_b32_e32 v97, 0xffff0000, v97
	v_lshlrev_b32_e32 v98, 16, v100
	v_and_b32_e32 v99, 0xffff0000, v100
	v_lshlrev_b32_e32 v100, 16, v101
	v_and_b32_e32 v101, 0xffff0000, v101
	v_lshlrev_b32_e32 v102, 16, v104
	v_and_b32_e32 v103, 0xffff0000, v104
	v_lshlrev_b32_e32 v104, 16, v105
	v_and_b32_e32 v105, 0xffff0000, v105
	v_lshlrev_b32_e32 v106, 16, v108
	v_and_b32_e32 v107, 0xffff0000, v108
	v_lshlrev_b32_e32 v108, 16, v109
	v_and_b32_e32 v109, 0xffff0000, v109
	v_lshlrev_b32_e32 v110, 16, v116
	v_and_b32_e32 v111, 0xffff0000, v116
	v_lshlrev_b32_e32 v116, 16, v117
	v_and_b32_e32 v117, 0xffff0000, v117
	v_lshlrev_b32_e32 v118, 16, v120
	v_and_b32_e32 v119, 0xffff0000, v120
	v_lshlrev_b32_e32 v120, 16, v121
	v_and_b32_e32 v121, 0xffff0000, v121
	v_lshlrev_b32_e32 v122, 16, v124
	v_and_b32_e32 v123, 0xffff0000, v124
	v_lshlrev_b32_e32 v124, 16, v125
	v_and_b32_e32 v125, 0xffff0000, v125
	v_lshlrev_b32_e32 v126, 16, v128
	v_and_b32_e32 v127, 0xffff0000, v128
	v_lshlrev_b32_e32 v128, 16, v129
	v_and_b32_e32 v129, 0xffff0000, v129
	v_lshlrev_b32_e32 v130, 16, v132
	v_and_b32_e32 v131, 0xffff0000, v132
	v_lshlrev_b32_e32 v132, 16, v133
	v_and_b32_e32 v133, 0xffff0000, v133
	v_lshlrev_b32_e32 v68, 16, v0
	v_and_b32_e32 v69, 0xffff0000, v0
	v_pk_fma_f32 v[68:69], v[16:17], v[72:73], v[68:69] op_sel_hi:[1,0,1] neg_lo:[1,0,0] neg_hi:[1,0,0]
	global_load_dwordx2 v[16:17], v[70:71], off offset:2048
	v_lshlrev_b32_e32 v0, 16, v1
	v_and_b32_e32 v1, 0xffff0000, v1
	v_pk_fma_f32 v[0:1], v[18:19], v[72:73], v[0:1] op_sel_hi:[1,0,1] neg_lo:[1,0,0] neg_hi:[1,0,0]
	v_lshlrev_b32_e32 v73, 2, v146
	v_pk_fma_f32 v[134:135], v[52:53], v[72:73], v[134:135] op_sel_hi:[1,0,1] neg_lo:[1,0,0] neg_hi:[1,0,0]
	v_pk_fma_f32 v[136:137], v[54:55], v[72:73], v[136:137] op_sel_hi:[1,0,1] neg_lo:[1,0,0] neg_hi:[1,0,0]
	v_pk_mul_f32 v[142:143], v[134:135], v[134:135]
	v_pk_mul_f32 v[140:141], v[136:137], v[136:137]
	v_pk_fma_f32 v[150:151], v[56:57], v[72:73], v[74:75] op_sel_hi:[1,0,1] neg_lo:[1,0,0] neg_hi:[1,0,0]
	v_pk_fma_f32 v[74:75], v[62:63], v[72:73], v[80:81] op_sel_hi:[1,0,1] neg_lo:[1,0,0] neg_hi:[1,0,0]
	v_pk_mul_f32 v[154:155], v[150:151], v[150:151]
	v_pk_mul_f32 v[80:81], v[74:75], v[74:75]
	v_pk_fma_f32 v[64:65], v[64:65], v[72:73], v[82:83] op_sel_hi:[1,0,1] neg_lo:[1,0,0] neg_hi:[1,0,0]
	v_pk_fma_f32 v[66:67], v[66:67], v[72:73], v[84:85] op_sel_hi:[1,0,1] neg_lo:[1,0,0] neg_hi:[1,0,0]
	v_pk_mul_f32 v[82:83], v[64:65], v[64:65]
	v_pk_mul_f32 v[84:85], v[66:67], v[66:67]
	v_pk_fma_f32 v[62:63], v[36:37], v[72:73], v[86:87] op_sel_hi:[1,0,1] neg_lo:[1,0,0] neg_hi:[1,0,0]
	v_pk_fma_f32 v[56:57], v[42:43], v[72:73], v[92:93] op_sel_hi:[1,0,1] neg_lo:[1,0,0] neg_hi:[1,0,0]
	v_pk_mul_f32 v[86:87], v[62:63], v[62:63]
	v_pk_mul_f32 v[92:93], v[56:57], v[56:57]
	v_pk_fma_f32 v[42:43], v[20:21], v[72:73], v[102:103] op_sel_hi:[1,0,1] neg_lo:[1,0,0] neg_hi:[1,0,0]
	v_pk_fma_f32 v[36:37], v[26:27], v[72:73], v[108:109] op_sel_hi:[1,0,1] neg_lo:[1,0,0] neg_hi:[1,0,0]
	v_pk_fma_f32 v[28:29], v[28:29], v[72:73], v[110:111] op_sel_hi:[1,0,1] neg_lo:[1,0,0] neg_hi:[1,0,0]
	v_pk_mul_f32 v[102:103], v[36:37], v[36:37]
	v_pk_mul_f32 v[108:109], v[28:29], v[28:29]
	v_pk_fma_f32 v[30:31], v[30:31], v[72:73], v[116:117] op_sel_hi:[1,0,1] neg_lo:[1,0,0] neg_hi:[1,0,0]
	v_pk_fma_f32 v[26:27], v[32:33], v[72:73], v[118:119] op_sel_hi:[1,0,1] neg_lo:[1,0,0] neg_hi:[1,0,0]
	v_pk_fma_f32 v[20:21], v[6:7], v[72:73], v[124:125] op_sel_hi:[1,0,1] neg_lo:[1,0,0] neg_hi:[1,0,0]
	v_pk_mul_f32 v[32:33], v[26:27], v[26:27]
	v_pk_mul_f32 v[110:111], v[20:21], v[20:21]
	v_pk_fma_f32 v[8:9], v[8:9], v[72:73], v[126:127] op_sel_hi:[1,0,1] neg_lo:[1,0,0] neg_hi:[1,0,0]
	v_pk_fma_f32 v[10:11], v[10:11], v[72:73], v[128:129] op_sel_hi:[1,0,1] neg_lo:[1,0,0] neg_hi:[1,0,0]
	v_pk_fma_f32 v[6:7], v[12:13], v[72:73], v[130:131] op_sel_hi:[1,0,1] neg_lo:[1,0,0] neg_hi:[1,0,0]
	v_pk_mul_f32 v[118:119], v[10:11], v[10:11]
	v_pk_mul_f32 v[12:13], v[6:7], v[6:7]
	v_pk_mul_f32 v[112:113], v[68:69], v[68:69]
	v_pk_mul_f32 v[114:115], v[0:1], v[0:1]
	s_waitcnt vmcnt(0)
	v_lshlrev_b32_e32 v2, 16, v16
	v_and_b32_e32 v138, 0xffff0000, v16
	v_mul_f32_e32 v52, 0xbfb8aa3b, v2
	v_mul_f32_e32 v53, 0xbfb8aa3b, v138
	v_exp_f32_e32 v52, v52
	v_exp_f32_e32 v53, v53
	v_lshlrev_b32_e32 v146, 16, v17
	v_and_b32_e32 v147, 0xffff0000, v17
	global_load_dwordx4 v[16:19], v73, s[38:39]
	v_pk_add_f32 v[52:53], v[52:53], 1.0 op_sel_hi:[1,0]
	s_nop 0
	v_div_scale_f32 v54, s[2:3], v53, v53, v138
	v_rcp_f32_e32 v55, v54
	s_nop 0
	v_fma_f32 v139, -v54, v55, 1.0
	v_fmac_f32_e32 v55, v139, v55
	v_div_scale_f32 v139, vcc, v138, v53, v138
	v_mul_f32_e32 v148, v139, v55
	v_fma_f32 v149, -v54, v148, v139
	v_fmac_f32_e32 v148, v149, v55
	v_fma_f32 v54, -v54, v148, v139
	v_div_fmas_f32 v54, v54, v55, v148
	v_div_fixup_f32 v139, v54, v53, v138
	v_div_scale_f32 v53, s[2:3], v52, v52, v2
	v_rcp_f32_e32 v54, v53
	s_nop 0
	v_fma_f32 v55, -v53, v54, 1.0
	v_fmac_f32_e32 v54, v55, v54
	v_div_scale_f32 v55, vcc, v2, v52, v2
	v_mul_f32_e32 v138, v55, v54
	v_fma_f32 v148, -v53, v138, v55
	v_fmac_f32_e32 v138, v148, v54
	v_fma_f32 v53, -v53, v138, v55
	v_div_fmas_f32 v53, v53, v54, v138
	v_div_fixup_f32 v138, v53, v52, v2
	v_mul_f32_e32 v2, 0xbfb8aa3b, v146
	v_exp_f32_e32 v52, v2
	v_mul_f32_e32 v2, 0xbfb8aa3b, v147
	v_exp_f32_e32 v53, v2
	s_nop 0
	v_pk_add_f32 v[52:53], v[52:53], 1.0 op_sel_hi:[1,0]
	s_nop 0
	v_div_scale_f32 v2, s[2:3], v53, v53, v147
	v_rcp_f32_e32 v54, v2
	s_nop 0
	v_fma_f32 v55, -v2, v54, 1.0
	v_fmac_f32_e32 v54, v55, v54
	v_div_scale_f32 v55, vcc, v147, v53, v147
	v_mul_f32_e32 v148, v55, v54
	v_fma_f32 v149, -v2, v148, v55
	v_fmac_f32_e32 v148, v149, v54
	v_fma_f32 v2, -v2, v148, v55
	v_div_fmas_f32 v2, v2, v54, v148
	v_div_fixup_f32 v149, v2, v53, v147
	v_div_scale_f32 v2, s[2:3], v52, v52, v146
	v_rcp_f32_e32 v53, v2
	s_nop 0
	v_fma_f32 v54, -v2, v53, 1.0
	v_fmac_f32_e32 v53, v54, v53
	v_div_scale_f32 v54, vcc, v146, v52, v146
	v_mul_f32_e32 v55, v54, v53
	v_fma_f32 v147, -v2, v55, v54
	v_fmac_f32_e32 v55, v147, v53
	v_fma_f32 v2, -v2, v55, v54
	v_div_fmas_f32 v2, v2, v53, v55
	v_div_fixup_f32 v148, v2, v52, v146
	v_add_f32_e32 v2, v142, v143
	v_add_f32_e32 v2, v140, v2
	v_add_f32_e32 v2, v141, v2
	v_pk_fma_f32 v[146:147], v[58:59], v[72:73], v[76:77] op_sel_hi:[1,0,1] neg_lo:[1,0,0] neg_hi:[1,0,0]
	v_add_f32_e32 v2, v154, v2
	v_pk_mul_f32 v[152:153], v[146:147], v[146:147]
	v_add_f32_e32 v2, v155, v2
	v_pk_fma_f32 v[76:77], v[60:61], v[72:73], v[78:79] op_sel_hi:[1,0,1] neg_lo:[1,0,0] neg_hi:[1,0,0]
	v_add_f32_e32 v2, v152, v2
	v_pk_mul_f32 v[78:79], v[76:77], v[76:77]
	v_add_f32_e32 v2, v153, v2
	v_add_f32_e32 v2, v78, v2
	v_add_f32_e32 v2, v79, v2
	v_add_f32_e32 v2, v80, v2
	v_add_f32_e32 v2, v81, v2
	v_add_f32_e32 v2, v82, v2
	v_add_f32_e32 v2, v83, v2
	v_add_f32_e32 v2, v84, v2
	v_add_f32_e32 v2, v85, v2
	v_pk_fma_f32 v[60:61], v[38:39], v[72:73], v[88:89] op_sel_hi:[1,0,1] neg_lo:[1,0,0] neg_hi:[1,0,0]
	v_add_f32_e32 v2, v86, v2
	v_pk_mul_f32 v[88:89], v[60:61], v[60:61]
	v_add_f32_e32 v2, v87, v2
	v_pk_fma_f32 v[58:59], v[40:41], v[72:73], v[90:91] op_sel_hi:[1,0,1] neg_lo:[1,0,0] neg_hi:[1,0,0]
	v_add_f32_e32 v2, v88, v2
	v_pk_mul_f32 v[90:91], v[58:59], v[58:59]
	v_add_f32_e32 v2, v89, v2
	v_add_f32_e32 v2, v90, v2
	v_add_f32_e32 v2, v91, v2
	v_pk_fma_f32 v[54:55], v[44:45], v[72:73], v[94:95] op_sel_hi:[1,0,1] neg_lo:[1,0,0] neg_hi:[1,0,0]
	v_add_f32_e32 v2, v92, v2
	v_pk_mul_f32 v[94:95], v[54:55], v[54:55]
	v_add_f32_e32 v2, v93, v2
	v_pk_fma_f32 v[52:53], v[46:47], v[72:73], v[96:97] op_sel_hi:[1,0,1] neg_lo:[1,0,0] neg_hi:[1,0,0]
	v_add_f32_e32 v2, v94, v2
	v_pk_mul_f32 v[96:97], v[52:53], v[52:53]
	v_add_f32_e32 v2, v95, v2
	v_pk_fma_f32 v[46:47], v[48:49], v[72:73], v[98:99] op_sel_hi:[1,0,1] neg_lo:[1,0,0] neg_hi:[1,0,0]
	v_add_f32_e32 v2, v96, v2
	v_pk_mul_f32 v[48:49], v[46:47], v[46:47]
	v_add_f32_e32 v2, v97, v2
	v_pk_fma_f32 v[44:45], v[50:51], v[72:73], v[100:101] op_sel_hi:[1,0,1] neg_lo:[1,0,0] neg_hi:[1,0,0]
	v_add_f32_e32 v2, v48, v2
	v_pk_mul_f32 v[50:51], v[44:45], v[44:45]
	v_add_f32_e32 v2, v49, v2
	v_add_f32_e32 v2, v50, v2
	v_pk_mul_f32 v[100:101], v[42:43], v[42:43]
	v_add_f32_e32 v2, v51, v2
	v_pk_fma_f32 v[40:41], v[22:23], v[72:73], v[104:105] op_sel_hi:[1,0,1] neg_lo:[1,0,0] neg_hi:[1,0,0]
	v_add_f32_e32 v2, v100, v2
	v_pk_mul_f32 v[98:99], v[40:41], v[40:41]
	v_add_f32_e32 v2, v101, v2
	v_pk_fma_f32 v[38:39], v[24:25], v[72:73], v[106:107] op_sel_hi:[1,0,1] neg_lo:[1,0,0] neg_hi:[1,0,0]
	v_add_f32_e32 v2, v98, v2
	v_pk_mul_f32 v[104:105], v[38:39], v[38:39]
	v_add_f32_e32 v2, v99, v2
	v_add_f32_e32 v2, v104, v2
	v_add_f32_e32 v2, v105, v2
	v_add_f32_e32 v2, v102, v2
	v_add_f32_e32 v2, v103, v2
	v_add_f32_e32 v2, v108, v2
	v_pk_mul_f32 v[106:107], v[30:31], v[30:31]
	v_add_f32_e32 v2, v109, v2
	v_add_f32_e32 v2, v106, v2
	v_add_f32_e32 v2, v107, v2
	v_pk_fma_f32 v[24:25], v[34:35], v[72:73], v[120:121] op_sel_hi:[1,0,1] neg_lo:[1,0,0] neg_hi:[1,0,0]
	v_add_f32_e32 v2, v32, v2
	v_pk_mul_f32 v[34:35], v[24:25], v[24:25]
	v_add_f32_e32 v2, v33, v2
	v_pk_fma_f32 v[22:23], v[4:5], v[72:73], v[122:123] op_sel_hi:[1,0,1] neg_lo:[1,0,0] neg_hi:[1,0,0]
	v_add_f32_e32 v2, v34, v2
	v_pk_mul_f32 v[116:117], v[22:23], v[22:23]
	v_add_f32_e32 v2, v35, v2
	v_add_f32_e32 v2, v116, v2
	v_add_f32_e32 v2, v117, v2
	v_add_f32_e32 v2, v110, v2
	v_pk_mul_f32 v[120:121], v[8:9], v[8:9]
	v_add_f32_e32 v2, v111, v2
	v_add_f32_e32 v2, v120, v2
	v_add_f32_e32 v2, v121, v2
	v_add_f32_e32 v2, v118, v2
	v_add_f32_e32 v2, v119, v2
	v_pk_fma_f32 v[4:5], v[14:15], v[72:73], v[132:133] op_sel_hi:[1,0,1] neg_lo:[1,0,0] neg_hi:[1,0,0]
	v_add_f32_e32 v2, v12, v2
	v_pk_mul_f32 v[14:15], v[4:5], v[4:5]
	v_add_f32_e32 v2, v13, v2
	v_add_f32_e32 v2, v14, v2
	v_add_f32_e32 v2, v15, v2
	v_add_f32_e32 v2, v112, v2
	v_add_f32_e32 v2, v113, v2
	v_add_f32_e32 v2, v114, v2
	v_add_f32_e32 v2, v115, v2
	ds_bpermute_b32 v12, v176, v2
	s_waitcnt lgkmcnt(0)
	v_add_f32_e32 v2, v2, v12
	v_mov_b32_e32 v12, 0x3727c5ac
	v_fmamk_f32 v2, v2, 0x3c000000, v12
	v_cmp_gt_f32_e32 vcc, s50, v2
	v_mul_f32_e32 v12, 0x4b800000, v2
	s_nop 0
	v_cndmask_b32_e32 v2, v2, v12, vcc
	v_rsq_f32_e32 v2, v2
	s_nop 0
	v_mul_f32_e32 v12, 0x45800000, v2
	v_cndmask_b32_e32 v2, v2, v12, vcc
	v_mul_f32_e32 v2, v161, v2
	v_pk_mul_f32 v[12:13], v[134:135], v[2:3] op_sel_hi:[1,0]
	v_pk_mul_f32 v[14:15], v[136:137], v[2:3] op_sel_hi:[1,0]
	s_waitcnt vmcnt(0)
	v_pk_mul_f32 v[12:13], v[16:17], v[12:13]
	v_pk_mul_f32 v[14:15], v[18:19], v[14:15]
	v_pk_mul_f32 v[12:13], v[138:139], v[12:13]
	v_pk_mul_f32 v[14:15], v[148:149], v[14:15]
	v_cvt_pk_bf16_f32 v12, v12, v13
	v_cvt_pk_bf16_f32 v13, v14, v15
	global_store_dwordx2 v[144:145], v[12:13], off
	global_load_dwordx2 v[16:17], v[70:71], off offset:2064
	s_nop 0
	global_load_dwordx4 v[12:15], v73, s[38:39] offset:32
	v_pk_mul_f32 v[32:33], v[150:151], v[2:3] op_sel_hi:[1,0]
	v_pk_mul_f32 v[28:29], v[28:29], v[2:3] op_sel_hi:[1,0]
	v_pk_mul_f32 v[26:27], v[26:27], v[2:3] op_sel_hi:[1,0]
	v_pk_mul_f32 v[22:23], v[22:23], v[2:3] op_sel_hi:[1,0]
	v_pk_mul_f32 v[8:9], v[8:9], v[2:3] op_sel_hi:[1,0]
	v_pk_mul_f32 v[10:11], v[10:11], v[2:3] op_sel_hi:[1,0]
	v_pk_mul_f32 v[6:7], v[6:7], v[2:3] op_sel_hi:[1,0]
	v_pk_mul_f32 v[4:5], v[4:5], v[2:3] op_sel_hi:[1,0]
	v_pk_mul_f32 v[0:1], v[0:1], v[2:3] op_sel_hi:[1,0]
	s_waitcnt vmcnt(1)
	v_lshlrev_b32_e32 v34, 16, v16
	v_and_b32_e32 v16, 0xffff0000, v16
	v_mul_f32_e32 v18, 0xbfb8aa3b, v34
	v_mul_f32_e32 v19, 0xbfb8aa3b, v16
	v_exp_f32_e32 v18, v18
	v_exp_f32_e32 v19, v19
	s_waitcnt vmcnt(0)
	v_pk_mul_f32 v[12:13], v[12:13], v[32:33]
	v_pk_add_f32 v[18:19], v[18:19], 1.0 op_sel_hi:[1,0]
	s_nop 0
	v_div_scale_f32 v32, s[2:3], v19, v19, v16
	v_rcp_f32_e32 v33, v32
	s_nop 0
	v_fma_f32 v35, -v32, v33, 1.0
	v_fmac_f32_e32 v33, v35, v33
	v_div_scale_f32 v35, vcc, v16, v19, v16
	v_mul_f32_e32 v48, v35, v33
	v_fma_f32 v49, -v32, v48, v35
	v_fmac_f32_e32 v48, v49, v33
	v_fma_f32 v32, -v32, v48, v35
	v_div_fmas_f32 v32, v32, v33, v48
	v_div_fixup_f32 v19, v32, v19, v16
	v_div_scale_f32 v16, s[2:3], v18, v18, v34
	v_rcp_f32_e32 v32, v16
	s_nop 0
	v_fma_f32 v33, -v16, v32, 1.0
	v_fmac_f32_e32 v32, v33, v32
	v_div_scale_f32 v33, vcc, v34, v18, v34
	v_mul_f32_e32 v35, v33, v32
	v_fma_f32 v48, -v16, v35, v33
	v_fmac_f32_e32 v35, v48, v32
	v_fma_f32 v16, -v16, v35, v33
	v_div_fmas_f32 v16, v16, v32, v35
	v_lshlrev_b32_e32 v32, 16, v17
	v_and_b32_e32 v33, 0xffff0000, v17
	v_div_fixup_f32 v18, v16, v18, v34
	v_mul_f32_e32 v16, 0xbfb8aa3b, v32
	v_mul_f32_e32 v17, 0xbfb8aa3b, v33
	v_exp_f32_e32 v16, v16
	v_exp_f32_e32 v17, v17
	v_pk_mul_f32 v[12:13], v[18:19], v[12:13]
	v_pk_mul_f32 v[18:19], v[146:147], v[2:3] op_sel_hi:[1,0]
	v_cvt_pk_bf16_f32 v12, v12, v13
	v_pk_add_f32 v[16:17], v[16:17], 1.0 op_sel_hi:[1,0]
	v_pk_mul_f32 v[14:15], v[14:15], v[18:19]
	v_div_scale_f32 v18, s[2:3], v17, v17, v33
	v_rcp_f32_e32 v19, v18
	s_nop 0
	v_fma_f32 v34, -v18, v19, 1.0
	v_fmac_f32_e32 v19, v34, v19
	v_div_scale_f32 v34, vcc, v33, v17, v33
	v_mul_f32_e32 v35, v34, v19
	v_fma_f32 v48, -v18, v35, v34
	v_fmac_f32_e32 v35, v48, v19
	v_fma_f32 v18, -v18, v35, v34
	v_div_fmas_f32 v18, v18, v19, v35
	v_div_fixup_f32 v17, v18, v17, v33
	v_div_scale_f32 v18, s[2:3], v16, v16, v32
	v_rcp_f32_e32 v19, v18
	s_nop 0
	v_fma_f32 v33, -v18, v19, 1.0
	v_fmac_f32_e32 v19, v33, v19
	v_div_scale_f32 v33, vcc, v32, v16, v32
	v_mul_f32_e32 v34, v33, v19
	v_fma_f32 v35, -v18, v34, v33
	v_fmac_f32_e32 v34, v35, v19
	v_fma_f32 v18, -v18, v34, v33
	v_div_fmas_f32 v18, v18, v19, v34
	v_div_fixup_f32 v16, v18, v16, v32
	v_pk_mul_f32 v[14:15], v[16:17], v[14:15]
	v_pk_mul_f32 v[32:33], v[76:77], v[2:3] op_sel_hi:[1,0]
	v_cvt_pk_bf16_f32 v13, v14, v15
	global_store_dwordx2 v[144:145], v[12:13], off offset:16
	global_load_dwordx2 v[16:17], v[70:71], off offset:2080
	s_nop 0
	global_load_dwordx4 v[12:15], v73, s[38:39] offset:64
	s_waitcnt vmcnt(1)
	v_lshlrev_b32_e32 v34, 16, v16
	v_and_b32_e32 v16, 0xffff0000, v16
	v_mul_f32_e32 v18, 0xbfb8aa3b, v34
	v_mul_f32_e32 v19, 0xbfb8aa3b, v16
	v_exp_f32_e32 v18, v18
	v_exp_f32_e32 v19, v19
	s_waitcnt vmcnt(0)
	v_pk_mul_f32 v[12:13], v[12:13], v[32:33]
	v_pk_add_f32 v[18:19], v[18:19], 1.0 op_sel_hi:[1,0]
	s_nop 0
	v_div_scale_f32 v32, s[2:3], v19, v19, v16
	v_rcp_f32_e32 v33, v32
	s_nop 0
	v_fma_f32 v35, -v32, v33, 1.0
	v_fmac_f32_e32 v33, v35, v33
	v_div_scale_f32 v35, vcc, v16, v19, v16
	v_mul_f32_e32 v48, v35, v33
	v_fma_f32 v49, -v32, v48, v35
	v_fmac_f32_e32 v48, v49, v33
	v_fma_f32 v32, -v32, v48, v35
	v_div_fmas_f32 v32, v32, v33, v48
	v_div_fixup_f32 v19, v32, v19, v16
	v_div_scale_f32 v16, s[2:3], v18, v18, v34
	v_rcp_f32_e32 v32, v16
	s_nop 0
	v_fma_f32 v33, -v16, v32, 1.0
	v_fmac_f32_e32 v32, v33, v32
	v_div_scale_f32 v33, vcc, v34, v18, v34
	v_mul_f32_e32 v35, v33, v32
	v_fma_f32 v48, -v16, v35, v33
	v_fmac_f32_e32 v35, v48, v32
	v_fma_f32 v16, -v16, v35, v33
	v_div_fmas_f32 v16, v16, v32, v35
	v_lshlrev_b32_e32 v32, 16, v17
	v_and_b32_e32 v33, 0xffff0000, v17
	v_div_fixup_f32 v18, v16, v18, v34
	v_mul_f32_e32 v16, 0xbfb8aa3b, v32
	v_mul_f32_e32 v17, 0xbfb8aa3b, v33
	v_exp_f32_e32 v16, v16
	v_exp_f32_e32 v17, v17
	v_pk_mul_f32 v[12:13], v[18:19], v[12:13]
	v_pk_mul_f32 v[18:19], v[74:75], v[2:3] op_sel_hi:[1,0]
	v_cvt_pk_bf16_f32 v12, v12, v13
	v_pk_add_f32 v[16:17], v[16:17], 1.0 op_sel_hi:[1,0]
	v_pk_mul_f32 v[14:15], v[14:15], v[18:19]
	v_div_scale_f32 v18, s[2:3], v17, v17, v33
	v_rcp_f32_e32 v19, v18
	s_nop 0
	v_fma_f32 v34, -v18, v19, 1.0
	v_fmac_f32_e32 v19, v34, v19
	v_div_scale_f32 v34, vcc, v33, v17, v33
	v_mul_f32_e32 v35, v34, v19
	v_fma_f32 v48, -v18, v35, v34
	v_fmac_f32_e32 v35, v48, v19
	v_fma_f32 v18, -v18, v35, v34
	v_div_fmas_f32 v18, v18, v19, v35
	v_div_fixup_f32 v17, v18, v17, v33
	v_div_scale_f32 v18, s[2:3], v16, v16, v32
	v_rcp_f32_e32 v19, v18
	s_nop 0
	v_fma_f32 v33, -v18, v19, 1.0
	v_fmac_f32_e32 v19, v33, v19
	v_div_scale_f32 v33, vcc, v32, v16, v32
	v_mul_f32_e32 v34, v33, v19
	v_fma_f32 v35, -v18, v34, v33
	v_fmac_f32_e32 v34, v35, v19
	v_fma_f32 v18, -v18, v34, v33
	v_div_fmas_f32 v18, v18, v19, v34
	v_div_fixup_f32 v16, v18, v16, v32
	v_pk_mul_f32 v[14:15], v[16:17], v[14:15]
	v_pk_mul_f32 v[32:33], v[64:65], v[2:3] op_sel_hi:[1,0]
	v_cvt_pk_bf16_f32 v13, v14, v15
	global_store_dwordx2 v[144:145], v[12:13], off offset:32
	global_load_dwordx2 v[16:17], v[70:71], off offset:2096
	s_nop 0
	global_load_dwordx4 v[12:15], v73, s[38:39] offset:96
	s_waitcnt vmcnt(1)
	v_lshlrev_b32_e32 v34, 16, v16
	v_and_b32_e32 v16, 0xffff0000, v16
	v_mul_f32_e32 v18, 0xbfb8aa3b, v34
	v_mul_f32_e32 v19, 0xbfb8aa3b, v16
	v_exp_f32_e32 v18, v18
	v_exp_f32_e32 v19, v19
	s_waitcnt vmcnt(0)
	v_pk_mul_f32 v[12:13], v[12:13], v[32:33]
	v_pk_add_f32 v[18:19], v[18:19], 1.0 op_sel_hi:[1,0]
	s_nop 0
	v_div_scale_f32 v32, s[2:3], v19, v19, v16
	v_rcp_f32_e32 v33, v32
	s_nop 0
	v_fma_f32 v35, -v32, v33, 1.0
	v_fmac_f32_e32 v33, v35, v33
	v_div_scale_f32 v35, vcc, v16, v19, v16
	v_mul_f32_e32 v48, v35, v33
	v_fma_f32 v49, -v32, v48, v35
	v_fmac_f32_e32 v48, v49, v33
	v_fma_f32 v32, -v32, v48, v35
	v_div_fmas_f32 v32, v32, v33, v48
	v_div_fixup_f32 v19, v32, v19, v16
	v_div_scale_f32 v16, s[2:3], v18, v18, v34
	v_rcp_f32_e32 v32, v16
	s_nop 0
	v_fma_f32 v33, -v16, v32, 1.0
	v_fmac_f32_e32 v32, v33, v32
	v_div_scale_f32 v33, vcc, v34, v18, v34
	v_mul_f32_e32 v35, v33, v32
	v_fma_f32 v48, -v16, v35, v33
	v_fmac_f32_e32 v35, v48, v32
	v_fma_f32 v16, -v16, v35, v33
	v_div_fmas_f32 v16, v16, v32, v35
	v_lshlrev_b32_e32 v32, 16, v17
	v_and_b32_e32 v33, 0xffff0000, v17
	v_div_fixup_f32 v18, v16, v18, v34
	v_mul_f32_e32 v16, 0xbfb8aa3b, v32
	v_mul_f32_e32 v17, 0xbfb8aa3b, v33
	v_exp_f32_e32 v16, v16
	v_exp_f32_e32 v17, v17
	v_pk_mul_f32 v[12:13], v[18:19], v[12:13]
	v_pk_mul_f32 v[18:19], v[66:67], v[2:3] op_sel_hi:[1,0]
	v_cvt_pk_bf16_f32 v12, v12, v13
	v_pk_add_f32 v[16:17], v[16:17], 1.0 op_sel_hi:[1,0]
	v_pk_mul_f32 v[14:15], v[14:15], v[18:19]
	v_div_scale_f32 v18, s[2:3], v17, v17, v33
	v_rcp_f32_e32 v19, v18
	s_nop 0
	v_fma_f32 v34, -v18, v19, 1.0
	v_fmac_f32_e32 v19, v34, v19
	v_div_scale_f32 v34, vcc, v33, v17, v33
	v_mul_f32_e32 v35, v34, v19
	v_fma_f32 v48, -v18, v35, v34
	v_fmac_f32_e32 v35, v48, v19
	v_fma_f32 v18, -v18, v35, v34
	v_div_fmas_f32 v18, v18, v19, v35
	v_div_fixup_f32 v17, v18, v17, v33
	v_div_scale_f32 v18, s[2:3], v16, v16, v32
	v_rcp_f32_e32 v19, v18
	s_nop 0
	v_fma_f32 v33, -v18, v19, 1.0
	v_fmac_f32_e32 v19, v33, v19
	v_div_scale_f32 v33, vcc, v32, v16, v32
	v_mul_f32_e32 v34, v33, v19
	v_fma_f32 v35, -v18, v34, v33
	v_fmac_f32_e32 v34, v35, v19
	v_fma_f32 v18, -v18, v34, v33
	v_div_fmas_f32 v18, v18, v19, v34
	v_div_fixup_f32 v16, v18, v16, v32
	v_pk_mul_f32 v[14:15], v[16:17], v[14:15]
	v_pk_mul_f32 v[32:33], v[62:63], v[2:3] op_sel_hi:[1,0]
	v_cvt_pk_bf16_f32 v13, v14, v15
	global_store_dwordx2 v[144:145], v[12:13], off offset:48
	global_load_dwordx2 v[16:17], v[70:71], off offset:2112
	s_nop 0
	global_load_dwordx4 v[12:15], v73, s[38:39] offset:128
	s_waitcnt vmcnt(1)
	v_lshlrev_b32_e32 v34, 16, v16
	v_and_b32_e32 v16, 0xffff0000, v16
	v_mul_f32_e32 v18, 0xbfb8aa3b, v34
	v_mul_f32_e32 v19, 0xbfb8aa3b, v16
	v_exp_f32_e32 v18, v18
	v_exp_f32_e32 v19, v19
	s_waitcnt vmcnt(0)
	v_pk_mul_f32 v[12:13], v[12:13], v[32:33]
	v_pk_add_f32 v[18:19], v[18:19], 1.0 op_sel_hi:[1,0]
	s_nop 0
	v_div_scale_f32 v32, s[2:3], v19, v19, v16
	v_rcp_f32_e32 v33, v32
	s_nop 0
	v_fma_f32 v35, -v32, v33, 1.0
	v_fmac_f32_e32 v33, v35, v33
	v_div_scale_f32 v35, vcc, v16, v19, v16
	v_mul_f32_e32 v48, v35, v33
	v_fma_f32 v49, -v32, v48, v35
	v_fmac_f32_e32 v48, v49, v33
	v_fma_f32 v32, -v32, v48, v35
	v_div_fmas_f32 v32, v32, v33, v48
	v_div_fixup_f32 v19, v32, v19, v16
	v_div_scale_f32 v16, s[2:3], v18, v18, v34
	v_rcp_f32_e32 v32, v16
	s_nop 0
	v_fma_f32 v33, -v16, v32, 1.0
	v_fmac_f32_e32 v32, v33, v32
	v_div_scale_f32 v33, vcc, v34, v18, v34
	v_mul_f32_e32 v35, v33, v32
	v_fma_f32 v48, -v16, v35, v33
	v_fmac_f32_e32 v35, v48, v32
	v_fma_f32 v16, -v16, v35, v33
	v_div_fmas_f32 v16, v16, v32, v35
	v_lshlrev_b32_e32 v32, 16, v17
	v_and_b32_e32 v33, 0xffff0000, v17
	v_div_fixup_f32 v18, v16, v18, v34
	v_mul_f32_e32 v16, 0xbfb8aa3b, v32
	v_mul_f32_e32 v17, 0xbfb8aa3b, v33
	v_exp_f32_e32 v16, v16
	v_exp_f32_e32 v17, v17
	v_pk_mul_f32 v[12:13], v[18:19], v[12:13]
	v_pk_mul_f32 v[18:19], v[60:61], v[2:3] op_sel_hi:[1,0]
	v_cvt_pk_bf16_f32 v12, v12, v13
	v_pk_add_f32 v[16:17], v[16:17], 1.0 op_sel_hi:[1,0]
	v_pk_mul_f32 v[14:15], v[14:15], v[18:19]
	v_div_scale_f32 v18, s[2:3], v17, v17, v33
	v_rcp_f32_e32 v19, v18
	s_nop 0
	v_fma_f32 v34, -v18, v19, 1.0
	v_fmac_f32_e32 v19, v34, v19
	v_div_scale_f32 v34, vcc, v33, v17, v33
	v_mul_f32_e32 v35, v34, v19
	v_fma_f32 v48, -v18, v35, v34
	v_fmac_f32_e32 v35, v48, v19
	v_fma_f32 v18, -v18, v35, v34
	v_div_fmas_f32 v18, v18, v19, v35
	v_div_fixup_f32 v17, v18, v17, v33
	v_div_scale_f32 v18, s[2:3], v16, v16, v32
	v_rcp_f32_e32 v19, v18
	s_nop 0
	v_fma_f32 v33, -v18, v19, 1.0
	v_fmac_f32_e32 v19, v33, v19
	v_div_scale_f32 v33, vcc, v32, v16, v32
	v_mul_f32_e32 v34, v33, v19
	v_fma_f32 v35, -v18, v34, v33
	v_fmac_f32_e32 v34, v35, v19
	v_fma_f32 v18, -v18, v34, v33
	v_div_fmas_f32 v18, v18, v19, v34
	v_div_fixup_f32 v16, v18, v16, v32
	v_pk_mul_f32 v[14:15], v[16:17], v[14:15]
	v_pk_mul_f32 v[32:33], v[58:59], v[2:3] op_sel_hi:[1,0]
	v_cvt_pk_bf16_f32 v13, v14, v15
	global_store_dwordx2 v[144:145], v[12:13], off offset:64
	global_load_dwordx2 v[16:17], v[70:71], off offset:2128
	s_nop 0
	global_load_dwordx4 v[12:15], v73, s[38:39] offset:160
	s_waitcnt vmcnt(1)
	v_lshlrev_b32_e32 v34, 16, v16
	v_and_b32_e32 v16, 0xffff0000, v16
	v_mul_f32_e32 v18, 0xbfb8aa3b, v34
	v_mul_f32_e32 v19, 0xbfb8aa3b, v16
	v_exp_f32_e32 v18, v18
	v_exp_f32_e32 v19, v19
	s_waitcnt vmcnt(0)
	v_pk_mul_f32 v[12:13], v[12:13], v[32:33]
	v_pk_add_f32 v[18:19], v[18:19], 1.0 op_sel_hi:[1,0]
	s_nop 0
	v_div_scale_f32 v32, s[2:3], v19, v19, v16
	v_rcp_f32_e32 v33, v32
	s_nop 0
	v_fma_f32 v35, -v32, v33, 1.0
	v_fmac_f32_e32 v33, v35, v33
	v_div_scale_f32 v35, vcc, v16, v19, v16
	v_mul_f32_e32 v48, v35, v33
	v_fma_f32 v49, -v32, v48, v35
	v_fmac_f32_e32 v48, v49, v33
	v_fma_f32 v32, -v32, v48, v35
	v_div_fmas_f32 v32, v32, v33, v48
	v_div_fixup_f32 v19, v32, v19, v16
	v_div_scale_f32 v16, s[2:3], v18, v18, v34
	v_rcp_f32_e32 v32, v16
	s_nop 0
	v_fma_f32 v33, -v16, v32, 1.0
	v_fmac_f32_e32 v32, v33, v32
	v_div_scale_f32 v33, vcc, v34, v18, v34
	v_mul_f32_e32 v35, v33, v32
	v_fma_f32 v48, -v16, v35, v33
	v_fmac_f32_e32 v35, v48, v32
	v_fma_f32 v16, -v16, v35, v33
	v_div_fmas_f32 v16, v16, v32, v35
	v_lshlrev_b32_e32 v32, 16, v17
	v_and_b32_e32 v33, 0xffff0000, v17
	v_div_fixup_f32 v18, v16, v18, v34
	v_mul_f32_e32 v16, 0xbfb8aa3b, v32
	v_mul_f32_e32 v17, 0xbfb8aa3b, v33
	v_exp_f32_e32 v16, v16
	v_exp_f32_e32 v17, v17
	v_pk_mul_f32 v[12:13], v[18:19], v[12:13]
	v_pk_mul_f32 v[18:19], v[56:57], v[2:3] op_sel_hi:[1,0]
	v_cvt_pk_bf16_f32 v12, v12, v13
	v_pk_add_f32 v[16:17], v[16:17], 1.0 op_sel_hi:[1,0]
	v_pk_mul_f32 v[14:15], v[14:15], v[18:19]
	v_div_scale_f32 v18, s[2:3], v17, v17, v33
	v_rcp_f32_e32 v19, v18
	s_nop 0
	v_fma_f32 v34, -v18, v19, 1.0
	v_fmac_f32_e32 v19, v34, v19
	v_div_scale_f32 v34, vcc, v33, v17, v33
	v_mul_f32_e32 v35, v34, v19
	v_fma_f32 v48, -v18, v35, v34
	v_fmac_f32_e32 v35, v48, v19
	v_fma_f32 v18, -v18, v35, v34
	v_div_fmas_f32 v18, v18, v19, v35
	v_div_fixup_f32 v17, v18, v17, v33
	v_div_scale_f32 v18, s[2:3], v16, v16, v32
	v_rcp_f32_e32 v19, v18
	s_nop 0
	v_fma_f32 v33, -v18, v19, 1.0
	v_fmac_f32_e32 v19, v33, v19
	v_div_scale_f32 v33, vcc, v32, v16, v32
	v_mul_f32_e32 v34, v33, v19
	v_fma_f32 v35, -v18, v34, v33
	v_fmac_f32_e32 v34, v35, v19
	v_fma_f32 v18, -v18, v34, v33
	v_div_fmas_f32 v18, v18, v19, v34
	v_div_fixup_f32 v16, v18, v16, v32
	v_pk_mul_f32 v[14:15], v[14:15], v[16:17]
	v_pk_mul_f32 v[32:33], v[54:55], v[2:3] op_sel_hi:[1,0]
	v_cvt_pk_bf16_f32 v13, v14, v15
	global_store_dwordx2 v[144:145], v[12:13], off offset:80
	global_load_dwordx2 v[16:17], v[70:71], off offset:2144
	s_nop 0
	global_load_dwordx4 v[12:15], v73, s[38:39] offset:192
	s_waitcnt vmcnt(1)
	v_lshlrev_b32_e32 v34, 16, v16
	v_and_b32_e32 v16, 0xffff0000, v16
	v_mul_f32_e32 v18, 0xbfb8aa3b, v34
	v_mul_f32_e32 v19, 0xbfb8aa3b, v16
	v_exp_f32_e32 v18, v18
	v_exp_f32_e32 v19, v19
	s_waitcnt vmcnt(0)
	v_pk_mul_f32 v[12:13], v[32:33], v[12:13]
	v_pk_add_f32 v[18:19], v[18:19], 1.0 op_sel_hi:[1,0]
	s_nop 0
	v_div_scale_f32 v32, s[2:3], v19, v19, v16
	v_rcp_f32_e32 v33, v32
	s_nop 0
	v_fma_f32 v35, -v32, v33, 1.0
	v_fmac_f32_e32 v33, v35, v33
	v_div_scale_f32 v35, vcc, v16, v19, v16
	v_mul_f32_e32 v48, v35, v33
	v_fma_f32 v49, -v32, v48, v35
	v_fmac_f32_e32 v48, v49, v33
	v_fma_f32 v32, -v32, v48, v35
	v_div_fmas_f32 v32, v32, v33, v48
	v_div_fixup_f32 v19, v32, v19, v16
	v_div_scale_f32 v16, s[2:3], v18, v18, v34
	v_rcp_f32_e32 v32, v16
	s_nop 0
	v_fma_f32 v33, -v16, v32, 1.0
	v_fmac_f32_e32 v32, v33, v32
	v_div_scale_f32 v33, vcc, v34, v18, v34
	v_mul_f32_e32 v35, v33, v32
	v_fma_f32 v48, -v16, v35, v33
	v_fmac_f32_e32 v35, v48, v32
	v_fma_f32 v16, -v16, v35, v33
	v_div_fmas_f32 v16, v16, v32, v35
	v_lshlrev_b32_e32 v32, 16, v17
	v_and_b32_e32 v33, 0xffff0000, v17
	v_div_fixup_f32 v18, v16, v18, v34
	v_mul_f32_e32 v16, 0xbfb8aa3b, v32
	v_mul_f32_e32 v17, 0xbfb8aa3b, v33
	v_exp_f32_e32 v16, v16
	v_exp_f32_e32 v17, v17
	v_pk_mul_f32 v[12:13], v[12:13], v[18:19]
	v_pk_mul_f32 v[18:19], v[52:53], v[2:3] op_sel_hi:[1,0]
	v_cvt_pk_bf16_f32 v12, v12, v13
	v_pk_add_f32 v[16:17], v[16:17], 1.0 op_sel_hi:[1,0]
	v_pk_mul_f32 v[14:15], v[18:19], v[14:15]
	v_div_scale_f32 v18, s[2:3], v17, v17, v33
	v_rcp_f32_e32 v19, v18
	s_nop 0
	v_fma_f32 v34, -v18, v19, 1.0
	v_fmac_f32_e32 v19, v34, v19
	v_div_scale_f32 v34, vcc, v33, v17, v33
	v_mul_f32_e32 v35, v34, v19
	v_fma_f32 v48, -v18, v35, v34
	v_fmac_f32_e32 v35, v48, v19
	v_fma_f32 v18, -v18, v35, v34
	v_div_fmas_f32 v18, v18, v19, v35
	v_div_fixup_f32 v17, v18, v17, v33
	v_div_scale_f32 v18, s[2:3], v16, v16, v32
	v_rcp_f32_e32 v19, v18
	s_nop 0
	v_fma_f32 v33, -v18, v19, 1.0
	v_fmac_f32_e32 v19, v33, v19
	v_div_scale_f32 v33, vcc, v32, v16, v32
	v_mul_f32_e32 v34, v33, v19
	v_fma_f32 v35, -v18, v34, v33
	v_fmac_f32_e32 v34, v35, v19
	v_fma_f32 v18, -v18, v34, v33
	v_div_fmas_f32 v18, v18, v19, v34
	v_div_fixup_f32 v16, v18, v16, v32
	v_pk_mul_f32 v[14:15], v[14:15], v[16:17]
	v_pk_mul_f32 v[32:33], v[46:47], v[2:3] op_sel_hi:[1,0]
	v_cvt_pk_bf16_f32 v13, v14, v15
	global_store_dwordx2 v[144:145], v[12:13], off offset:96
	global_load_dwordx2 v[16:17], v[70:71], off offset:2160
	s_nop 0
	global_load_dwordx4 v[12:15], v73, s[38:39] offset:224
	s_waitcnt vmcnt(1)
	v_lshlrev_b32_e32 v34, 16, v16
	v_and_b32_e32 v16, 0xffff0000, v16
	v_mul_f32_e32 v18, 0xbfb8aa3b, v34
	v_mul_f32_e32 v19, 0xbfb8aa3b, v16
	v_exp_f32_e32 v18, v18
	v_exp_f32_e32 v19, v19
	s_waitcnt vmcnt(0)
	v_pk_mul_f32 v[12:13], v[32:33], v[12:13]
	v_pk_add_f32 v[18:19], v[18:19], 1.0 op_sel_hi:[1,0]
	s_nop 0
	v_div_scale_f32 v32, s[2:3], v19, v19, v16
	v_rcp_f32_e32 v33, v32
	s_nop 0
	v_fma_f32 v35, -v32, v33, 1.0
	v_fmac_f32_e32 v33, v35, v33
	v_div_scale_f32 v35, vcc, v16, v19, v16
	v_mul_f32_e32 v46, v35, v33
	v_fma_f32 v47, -v32, v46, v35
	v_fmac_f32_e32 v46, v47, v33
	v_fma_f32 v32, -v32, v46, v35
	v_div_fmas_f32 v32, v32, v33, v46
	v_div_fixup_f32 v19, v32, v19, v16
	v_div_scale_f32 v16, s[2:3], v18, v18, v34
	v_rcp_f32_e32 v32, v16
	s_nop 0
	v_fma_f32 v33, -v16, v32, 1.0
	v_fmac_f32_e32 v32, v33, v32
	v_div_scale_f32 v33, vcc, v34, v18, v34
	v_mul_f32_e32 v35, v33, v32
	v_fma_f32 v46, -v16, v35, v33
	v_fmac_f32_e32 v35, v46, v32
	v_fma_f32 v16, -v16, v35, v33
	v_div_fmas_f32 v16, v16, v32, v35
	v_lshlrev_b32_e32 v32, 16, v17
	v_and_b32_e32 v33, 0xffff0000, v17
	v_div_fixup_f32 v18, v16, v18, v34
	v_mul_f32_e32 v16, 0xbfb8aa3b, v32
	v_mul_f32_e32 v17, 0xbfb8aa3b, v33
	v_exp_f32_e32 v16, v16
	v_exp_f32_e32 v17, v17
	v_pk_mul_f32 v[12:13], v[12:13], v[18:19]
	v_pk_mul_f32 v[18:19], v[44:45], v[2:3] op_sel_hi:[1,0]
	v_cvt_pk_bf16_f32 v12, v12, v13
	v_pk_add_f32 v[16:17], v[16:17], 1.0 op_sel_hi:[1,0]
	v_pk_mul_f32 v[14:15], v[18:19], v[14:15]
	v_div_scale_f32 v18, s[2:3], v17, v17, v33
	v_rcp_f32_e32 v19, v18
	s_nop 0
	v_fma_f32 v34, -v18, v19, 1.0
	v_fmac_f32_e32 v19, v34, v19
	v_div_scale_f32 v34, vcc, v33, v17, v33
	v_mul_f32_e32 v35, v34, v19
	v_fma_f32 v44, -v18, v35, v34
	v_fmac_f32_e32 v35, v44, v19
	v_fma_f32 v18, -v18, v35, v34
	v_div_fmas_f32 v18, v18, v19, v35
	v_div_fixup_f32 v17, v18, v17, v33
	v_div_scale_f32 v18, s[2:3], v16, v16, v32
	v_rcp_f32_e32 v19, v18
	s_nop 0
	v_fma_f32 v33, -v18, v19, 1.0
	v_fmac_f32_e32 v19, v33, v19
	v_div_scale_f32 v33, vcc, v32, v16, v32
	v_mul_f32_e32 v34, v33, v19
	v_fma_f32 v35, -v18, v34, v33
	v_fmac_f32_e32 v34, v35, v19
	v_fma_f32 v18, -v18, v34, v33
	v_div_fmas_f32 v18, v18, v19, v34
	v_div_fixup_f32 v16, v18, v16, v32
	v_pk_mul_f32 v[14:15], v[14:15], v[16:17]
	v_pk_mul_f32 v[32:33], v[42:43], v[2:3] op_sel_hi:[1,0]
	v_cvt_pk_bf16_f32 v13, v14, v15
	global_store_dwordx2 v[144:145], v[12:13], off offset:112
	global_load_dwordx2 v[16:17], v[70:71], off offset:2176
	s_nop 0
	global_load_dwordx4 v[12:15], v73, s[38:39] offset:256
	s_waitcnt vmcnt(1)
	v_lshlrev_b32_e32 v34, 16, v16
	v_and_b32_e32 v16, 0xffff0000, v16
	v_mul_f32_e32 v18, 0xbfb8aa3b, v34
	v_mul_f32_e32 v19, 0xbfb8aa3b, v16
	v_exp_f32_e32 v18, v18
	v_exp_f32_e32 v19, v19
	s_waitcnt vmcnt(0)
	v_pk_mul_f32 v[12:13], v[32:33], v[12:13]
	v_pk_add_f32 v[18:19], v[18:19], 1.0 op_sel_hi:[1,0]
	s_nop 0
	v_div_scale_f32 v32, s[2:3], v19, v19, v16
	v_rcp_f32_e32 v33, v32
	s_nop 0
	v_fma_f32 v35, -v32, v33, 1.0
	v_fmac_f32_e32 v33, v35, v33
	v_div_scale_f32 v35, vcc, v16, v19, v16
	v_mul_f32_e32 v42, v35, v33
	v_fma_f32 v43, -v32, v42, v35
	v_fmac_f32_e32 v42, v43, v33
	v_fma_f32 v32, -v32, v42, v35
	v_div_fmas_f32 v32, v32, v33, v42
	v_div_fixup_f32 v19, v32, v19, v16
	v_div_scale_f32 v16, s[2:3], v18, v18, v34
	v_rcp_f32_e32 v32, v16
	s_nop 0
	v_fma_f32 v33, -v16, v32, 1.0
	v_fmac_f32_e32 v32, v33, v32
	v_div_scale_f32 v33, vcc, v34, v18, v34
	v_mul_f32_e32 v35, v33, v32
	v_fma_f32 v42, -v16, v35, v33
	v_fmac_f32_e32 v35, v42, v32
	v_fma_f32 v16, -v16, v35, v33
	v_div_fmas_f32 v16, v16, v32, v35
	v_lshlrev_b32_e32 v32, 16, v17
	v_and_b32_e32 v33, 0xffff0000, v17
	v_div_fixup_f32 v18, v16, v18, v34
	v_mul_f32_e32 v16, 0xbfb8aa3b, v32
	v_mul_f32_e32 v17, 0xbfb8aa3b, v33
	v_exp_f32_e32 v16, v16
	v_exp_f32_e32 v17, v17
	v_pk_mul_f32 v[12:13], v[12:13], v[18:19]
	v_pk_mul_f32 v[18:19], v[40:41], v[2:3] op_sel_hi:[1,0]
	v_cvt_pk_bf16_f32 v12, v12, v13
	v_pk_add_f32 v[16:17], v[16:17], 1.0 op_sel_hi:[1,0]
	v_pk_mul_f32 v[14:15], v[18:19], v[14:15]
	v_div_scale_f32 v18, s[2:3], v17, v17, v33
	v_rcp_f32_e32 v19, v18
	s_nop 0
	v_fma_f32 v34, -v18, v19, 1.0
	v_fmac_f32_e32 v19, v34, v19
	v_div_scale_f32 v34, vcc, v33, v17, v33
	v_mul_f32_e32 v35, v34, v19
	v_fma_f32 v40, -v18, v35, v34
	v_fmac_f32_e32 v35, v40, v19
	v_fma_f32 v18, -v18, v35, v34
	v_div_fmas_f32 v18, v18, v19, v35
	v_div_fixup_f32 v17, v18, v17, v33
	v_div_scale_f32 v18, s[2:3], v16, v16, v32
	v_rcp_f32_e32 v19, v18
	s_nop 0
	v_fma_f32 v33, -v18, v19, 1.0
	v_fmac_f32_e32 v19, v33, v19
	v_div_scale_f32 v33, vcc, v32, v16, v32
	v_mul_f32_e32 v34, v33, v19
	v_fma_f32 v35, -v18, v34, v33
	v_fmac_f32_e32 v34, v35, v19
	v_fma_f32 v18, -v18, v34, v33
	v_div_fmas_f32 v18, v18, v19, v34
	v_div_fixup_f32 v16, v18, v16, v32
	v_pk_mul_f32 v[14:15], v[14:15], v[16:17]
	v_pk_mul_f32 v[32:33], v[38:39], v[2:3] op_sel_hi:[1,0]
	v_cvt_pk_bf16_f32 v13, v14, v15
	global_store_dwordx2 v[144:145], v[12:13], off offset:128
	global_load_dwordx2 v[16:17], v[70:71], off offset:2192
	s_nop 0
	global_load_dwordx4 v[12:15], v73, s[38:39] offset:288
	s_waitcnt vmcnt(1)
	v_lshlrev_b32_e32 v34, 16, v16
	v_and_b32_e32 v16, 0xffff0000, v16
	v_mul_f32_e32 v18, 0xbfb8aa3b, v34
	v_mul_f32_e32 v19, 0xbfb8aa3b, v16
	v_exp_f32_e32 v18, v18
	v_exp_f32_e32 v19, v19
	s_waitcnt vmcnt(0)
	v_pk_mul_f32 v[12:13], v[32:33], v[12:13]
	v_pk_add_f32 v[18:19], v[18:19], 1.0 op_sel_hi:[1,0]
	s_nop 0
	v_div_scale_f32 v32, s[2:3], v19, v19, v16
	v_rcp_f32_e32 v33, v32
	s_nop 0
	v_fma_f32 v35, -v32, v33, 1.0
	v_fmac_f32_e32 v33, v35, v33
	v_div_scale_f32 v35, vcc, v16, v19, v16
	v_mul_f32_e32 v38, v35, v33
	v_fma_f32 v39, -v32, v38, v35
	v_fmac_f32_e32 v38, v39, v33
	v_fma_f32 v32, -v32, v38, v35
	v_div_fmas_f32 v32, v32, v33, v38
	v_div_fixup_f32 v19, v32, v19, v16
	v_div_scale_f32 v16, s[2:3], v18, v18, v34
	v_rcp_f32_e32 v32, v16
	s_nop 0
	v_fma_f32 v33, -v16, v32, 1.0
	v_fmac_f32_e32 v32, v33, v32
	v_div_scale_f32 v33, vcc, v34, v18, v34
	v_mul_f32_e32 v35, v33, v32
	v_fma_f32 v38, -v16, v35, v33
	v_fmac_f32_e32 v35, v38, v32
	v_fma_f32 v16, -v16, v35, v33
	v_div_fmas_f32 v16, v16, v32, v35
	v_lshlrev_b32_e32 v32, 16, v17
	v_and_b32_e32 v33, 0xffff0000, v17
	v_div_fixup_f32 v18, v16, v18, v34
	v_mul_f32_e32 v16, 0xbfb8aa3b, v32
	v_mul_f32_e32 v17, 0xbfb8aa3b, v33
	v_exp_f32_e32 v16, v16
	v_exp_f32_e32 v17, v17
	v_pk_mul_f32 v[12:13], v[12:13], v[18:19]
	v_pk_mul_f32 v[18:19], v[36:37], v[2:3] op_sel_hi:[1,0]
	v_cvt_pk_bf16_f32 v12, v12, v13
	v_pk_add_f32 v[16:17], v[16:17], 1.0 op_sel_hi:[1,0]
	v_pk_mul_f32 v[14:15], v[18:19], v[14:15]
	v_div_scale_f32 v18, s[2:3], v17, v17, v33
	v_rcp_f32_e32 v19, v18
	s_nop 0
	v_fma_f32 v34, -v18, v19, 1.0
	v_fmac_f32_e32 v19, v34, v19
	v_div_scale_f32 v34, vcc, v33, v17, v33
	v_mul_f32_e32 v35, v34, v19
	v_fma_f32 v36, -v18, v35, v34
	v_fmac_f32_e32 v35, v36, v19
	v_fma_f32 v18, -v18, v35, v34
	v_div_fmas_f32 v18, v18, v19, v35
	v_div_fixup_f32 v17, v18, v17, v33
	v_div_scale_f32 v18, s[2:3], v16, v16, v32
	v_rcp_f32_e32 v19, v18
	s_nop 0
	v_fma_f32 v33, -v18, v19, 1.0
	v_fmac_f32_e32 v19, v33, v19
	v_div_scale_f32 v33, vcc, v32, v16, v32
	v_mul_f32_e32 v34, v33, v19
	v_fma_f32 v35, -v18, v34, v33
	v_fmac_f32_e32 v34, v35, v19
	v_fma_f32 v18, -v18, v34, v33
	v_div_fmas_f32 v18, v18, v19, v34
	v_div_fixup_f32 v16, v18, v16, v32
	v_pk_mul_f32 v[14:15], v[14:15], v[16:17]
	s_nop 0
	v_cvt_pk_bf16_f32 v13, v14, v15
	global_store_dwordx2 v[144:145], v[12:13], off offset:144
	global_load_dwordx2 v[16:17], v[70:71], off offset:2208
	s_nop 0
	global_load_dwordx4 v[12:15], v73, s[38:39] offset:320
	s_waitcnt vmcnt(1)
	v_lshlrev_b32_e32 v32, 16, v16
	v_and_b32_e32 v16, 0xffff0000, v16
	v_mul_f32_e32 v18, 0xbfb8aa3b, v32
	v_mul_f32_e32 v19, 0xbfb8aa3b, v16
	v_exp_f32_e32 v18, v18
	v_exp_f32_e32 v19, v19
	s_waitcnt vmcnt(0)
	v_pk_mul_f32 v[12:13], v[28:29], v[12:13]
	v_pk_add_f32 v[18:19], v[18:19], 1.0 op_sel_hi:[1,0]
	s_nop 0
	v_div_scale_f32 v28, s[2:3], v19, v19, v16
	v_rcp_f32_e32 v29, v28
	s_nop 0
	v_fma_f32 v33, -v28, v29, 1.0
	v_fmac_f32_e32 v29, v33, v29
	v_div_scale_f32 v33, vcc, v16, v19, v16
	v_mul_f32_e32 v34, v33, v29
	v_fma_f32 v35, -v28, v34, v33
	v_fmac_f32_e32 v34, v35, v29
	v_fma_f32 v28, -v28, v34, v33
	v_div_fmas_f32 v28, v28, v29, v34
	v_div_fixup_f32 v19, v28, v19, v16
	v_div_scale_f32 v16, s[2:3], v18, v18, v32
	v_rcp_f32_e32 v28, v16
	s_nop 0
	v_fma_f32 v29, -v16, v28, 1.0
	v_fmac_f32_e32 v28, v29, v28
	v_div_scale_f32 v29, vcc, v32, v18, v32
	v_mul_f32_e32 v33, v29, v28
	v_fma_f32 v34, -v16, v33, v29
	v_fmac_f32_e32 v33, v34, v28
	v_fma_f32 v16, -v16, v33, v29
	v_div_fmas_f32 v16, v16, v28, v33
	v_lshlrev_b32_e32 v28, 16, v17
	v_and_b32_e32 v29, 0xffff0000, v17
	v_div_fixup_f32 v18, v16, v18, v32
	v_mul_f32_e32 v16, 0xbfb8aa3b, v28
	v_mul_f32_e32 v17, 0xbfb8aa3b, v29
	v_exp_f32_e32 v16, v16
	v_exp_f32_e32 v17, v17
	v_pk_mul_f32 v[12:13], v[12:13], v[18:19]
	v_pk_mul_f32 v[18:19], v[30:31], v[2:3] op_sel_hi:[1,0]
	v_cvt_pk_bf16_f32 v12, v12, v13
	v_pk_add_f32 v[16:17], v[16:17], 1.0 op_sel_hi:[1,0]
	v_pk_mul_f32 v[14:15], v[18:19], v[14:15]
	v_div_scale_f32 v18, s[2:3], v17, v17, v29
	v_rcp_f32_e32 v19, v18
	s_nop 0
	v_fma_f32 v30, -v18, v19, 1.0
	v_fmac_f32_e32 v19, v30, v19
	v_div_scale_f32 v30, vcc, v29, v17, v29
	v_mul_f32_e32 v31, v30, v19
	v_fma_f32 v32, -v18, v31, v30
	v_fmac_f32_e32 v31, v32, v19
	v_fma_f32 v18, -v18, v31, v30
	v_div_fmas_f32 v18, v18, v19, v31
	v_div_fixup_f32 v17, v18, v17, v29
	v_div_scale_f32 v18, s[2:3], v16, v16, v28
	v_rcp_f32_e32 v19, v18
	s_nop 0
	v_fma_f32 v29, -v18, v19, 1.0
	v_fmac_f32_e32 v19, v29, v19
	v_div_scale_f32 v29, vcc, v28, v16, v28
	v_mul_f32_e32 v30, v29, v19
	v_fma_f32 v31, -v18, v30, v29
	v_fmac_f32_e32 v30, v31, v19
	v_fma_f32 v18, -v18, v30, v29
	v_div_fmas_f32 v18, v18, v19, v30
	v_div_fixup_f32 v16, v18, v16, v28
	v_pk_mul_f32 v[14:15], v[14:15], v[16:17]
	s_nop 0
	v_cvt_pk_bf16_f32 v13, v14, v15
	global_store_dwordx2 v[144:145], v[12:13], off offset:160
	global_load_dwordx2 v[16:17], v[70:71], off offset:2224
	s_nop 0
	global_load_dwordx4 v[12:15], v73, s[38:39] offset:352
	s_waitcnt vmcnt(1)
	v_lshlrev_b32_e32 v28, 16, v16
	v_and_b32_e32 v16, 0xffff0000, v16
	v_mul_f32_e32 v18, 0xbfb8aa3b, v28
	v_mul_f32_e32 v19, 0xbfb8aa3b, v16
	v_exp_f32_e32 v18, v18
	v_exp_f32_e32 v19, v19
	s_waitcnt vmcnt(0)
	v_pk_mul_f32 v[12:13], v[26:27], v[12:13]
	v_pk_add_f32 v[18:19], v[18:19], 1.0 op_sel_hi:[1,0]
	s_nop 0
	v_div_scale_f32 v26, s[2:3], v19, v19, v16
	v_rcp_f32_e32 v27, v26
	s_nop 0
	v_fma_f32 v29, -v26, v27, 1.0
	v_fmac_f32_e32 v27, v29, v27
	v_div_scale_f32 v29, vcc, v16, v19, v16
	v_mul_f32_e32 v30, v29, v27
	v_fma_f32 v31, -v26, v30, v29
	v_fmac_f32_e32 v30, v31, v27
	v_fma_f32 v26, -v26, v30, v29
	v_div_fmas_f32 v26, v26, v27, v30
	v_div_fixup_f32 v19, v26, v19, v16
	v_div_scale_f32 v16, s[2:3], v18, v18, v28
	v_rcp_f32_e32 v26, v16
	s_nop 0
	v_fma_f32 v27, -v16, v26, 1.0
	v_fmac_f32_e32 v26, v27, v26
	v_div_scale_f32 v27, vcc, v28, v18, v28
	v_mul_f32_e32 v29, v27, v26
	v_fma_f32 v30, -v16, v29, v27
	v_fmac_f32_e32 v29, v30, v26
	v_fma_f32 v16, -v16, v29, v27
	v_div_fmas_f32 v16, v16, v26, v29
	v_lshlrev_b32_e32 v26, 16, v17
	v_and_b32_e32 v27, 0xffff0000, v17
	v_div_fixup_f32 v18, v16, v18, v28
	v_mul_f32_e32 v16, 0xbfb8aa3b, v26
	v_mul_f32_e32 v17, 0xbfb8aa3b, v27
	v_exp_f32_e32 v16, v16
	v_exp_f32_e32 v17, v17
	v_pk_mul_f32 v[12:13], v[12:13], v[18:19]
	v_pk_mul_f32 v[18:19], v[24:25], v[2:3] op_sel_hi:[1,0]
	v_cvt_pk_bf16_f32 v12, v12, v13
	v_pk_add_f32 v[16:17], v[16:17], 1.0 op_sel_hi:[1,0]
	v_pk_mul_f32 v[14:15], v[18:19], v[14:15]
	v_div_scale_f32 v18, s[2:3], v17, v17, v27
	v_rcp_f32_e32 v19, v18
	s_nop 0
	v_fma_f32 v24, -v18, v19, 1.0
	v_fmac_f32_e32 v19, v24, v19
	v_div_scale_f32 v24, vcc, v27, v17, v27
	v_mul_f32_e32 v25, v24, v19
	v_fma_f32 v28, -v18, v25, v24
	v_fmac_f32_e32 v25, v28, v19
	v_fma_f32 v18, -v18, v25, v24
	v_div_fmas_f32 v18, v18, v19, v25
	v_div_fixup_f32 v17, v18, v17, v27
	v_div_scale_f32 v18, s[2:3], v16, v16, v26
	v_rcp_f32_e32 v19, v18
	s_nop 0
	v_fma_f32 v24, -v18, v19, 1.0
	v_fmac_f32_e32 v19, v24, v19
	v_div_scale_f32 v24, vcc, v26, v16, v26
	v_mul_f32_e32 v25, v24, v19
	v_fma_f32 v27, -v18, v25, v24
	v_fmac_f32_e32 v25, v27, v19
	v_fma_f32 v18, -v18, v25, v24
	v_div_fmas_f32 v18, v18, v19, v25
	v_div_fixup_f32 v16, v18, v16, v26
	v_pk_mul_f32 v[14:15], v[14:15], v[16:17]
	s_nop 0
	v_cvt_pk_bf16_f32 v13, v14, v15
	global_store_dwordx2 v[144:145], v[12:13], off offset:176
	global_load_dwordx2 v[16:17], v[70:71], off offset:2240
	s_nop 0
	global_load_dwordx4 v[12:15], v73, s[38:39] offset:384
	s_waitcnt vmcnt(1)
	v_lshlrev_b32_e32 v24, 16, v16
	v_and_b32_e32 v16, 0xffff0000, v16
	v_mul_f32_e32 v18, 0xbfb8aa3b, v24
	v_mul_f32_e32 v19, 0xbfb8aa3b, v16
	v_exp_f32_e32 v18, v18
	v_exp_f32_e32 v19, v19
	s_waitcnt vmcnt(0)
	v_pk_mul_f32 v[12:13], v[22:23], v[12:13]
	v_pk_add_f32 v[18:19], v[18:19], 1.0 op_sel_hi:[1,0]
	s_nop 0
	v_div_scale_f32 v22, s[2:3], v19, v19, v16
	v_rcp_f32_e32 v23, v22
	s_nop 0
	v_fma_f32 v25, -v22, v23, 1.0
	v_fmac_f32_e32 v23, v25, v23
	v_div_scale_f32 v25, vcc, v16, v19, v16
	v_mul_f32_e32 v26, v25, v23
	v_fma_f32 v27, -v22, v26, v25
	v_fmac_f32_e32 v26, v27, v23
	v_fma_f32 v22, -v22, v26, v25
	v_div_fmas_f32 v22, v22, v23, v26
	v_div_fixup_f32 v19, v22, v19, v16
	v_div_scale_f32 v16, s[2:3], v18, v18, v24
	v_rcp_f32_e32 v22, v16
	s_nop 0
	v_fma_f32 v23, -v16, v22, 1.0
	v_fmac_f32_e32 v22, v23, v22
	v_div_scale_f32 v23, vcc, v24, v18, v24
	v_mul_f32_e32 v25, v23, v22
	v_fma_f32 v26, -v16, v25, v23
	v_fmac_f32_e32 v25, v26, v22
	v_fma_f32 v16, -v16, v25, v23
	v_div_fmas_f32 v16, v16, v22, v25
	v_lshlrev_b32_e32 v22, 16, v17
	v_and_b32_e32 v23, 0xffff0000, v17
	v_div_fixup_f32 v18, v16, v18, v24
	v_mul_f32_e32 v16, 0xbfb8aa3b, v22
	v_mul_f32_e32 v17, 0xbfb8aa3b, v23
	v_exp_f32_e32 v16, v16
	v_exp_f32_e32 v17, v17
	v_pk_mul_f32 v[12:13], v[12:13], v[18:19]
	v_pk_mul_f32 v[18:19], v[20:21], v[2:3] op_sel_hi:[1,0]
	v_cvt_pk_bf16_f32 v12, v12, v13
	v_pk_add_f32 v[16:17], v[16:17], 1.0 op_sel_hi:[1,0]
	v_pk_mul_f32 v[14:15], v[18:19], v[14:15]
	v_div_scale_f32 v18, s[2:3], v17, v17, v23
	v_rcp_f32_e32 v19, v18
	s_nop 0
	v_fma_f32 v20, -v18, v19, 1.0
	v_fmac_f32_e32 v19, v20, v19
	v_div_scale_f32 v20, vcc, v23, v17, v23
	v_mul_f32_e32 v21, v20, v19
	v_fma_f32 v24, -v18, v21, v20
	v_fmac_f32_e32 v21, v24, v19
	v_fma_f32 v18, -v18, v21, v20
	v_div_fmas_f32 v18, v18, v19, v21
	v_div_fixup_f32 v17, v18, v17, v23
	v_div_scale_f32 v18, s[2:3], v16, v16, v22
	v_rcp_f32_e32 v19, v18
	s_nop 0
	v_fma_f32 v20, -v18, v19, 1.0
	v_fmac_f32_e32 v19, v20, v19
	v_div_scale_f32 v20, vcc, v22, v16, v22
	v_mul_f32_e32 v21, v20, v19
	v_fma_f32 v23, -v18, v21, v20
	v_fmac_f32_e32 v21, v23, v19
	v_fma_f32 v18, -v18, v21, v20
	v_div_fmas_f32 v18, v18, v19, v21
	v_div_fixup_f32 v16, v18, v16, v22
	v_pk_mul_f32 v[14:15], v[14:15], v[16:17]
	s_nop 0
	v_cvt_pk_bf16_f32 v13, v14, v15
	global_store_dwordx2 v[144:145], v[12:13], off offset:192
	global_load_dwordx2 v[16:17], v[70:71], off offset:2256
	s_nop 0
	global_load_dwordx4 v[12:15], v73, s[38:39] offset:416
	s_waitcnt vmcnt(1)
	v_lshlrev_b32_e32 v20, 16, v16
	v_and_b32_e32 v16, 0xffff0000, v16
	v_mul_f32_e32 v18, 0xbfb8aa3b, v20
	s_waitcnt vmcnt(0)
	v_pk_mul_f32 v[8:9], v[8:9], v[12:13]
	v_mul_f32_e32 v12, 0xbfb8aa3b, v16
	v_exp_f32_e32 v18, v18
	v_exp_f32_e32 v19, v12
	v_pk_mul_f32 v[10:11], v[10:11], v[14:15]
	v_pk_add_f32 v[12:13], v[18:19], 1.0 op_sel_hi:[1,0]
	s_nop 0
	v_div_scale_f32 v18, s[2:3], v13, v13, v16
	v_rcp_f32_e32 v19, v18
	s_nop 0
	v_fma_f32 v21, -v18, v19, 1.0
	v_fmac_f32_e32 v19, v21, v19
	v_div_scale_f32 v21, vcc, v16, v13, v16
	v_mul_f32_e32 v22, v21, v19
	v_fma_f32 v23, -v18, v22, v21
	v_fmac_f32_e32 v22, v23, v19
	v_fma_f32 v18, -v18, v22, v21
	v_div_fmas_f32 v18, v18, v19, v22
	v_div_fixup_f32 v13, v18, v13, v16
	v_div_scale_f32 v16, s[2:3], v12, v12, v20
	v_rcp_f32_e32 v18, v16
	s_nop 0
	v_fma_f32 v19, -v16, v18, 1.0
	v_fmac_f32_e32 v18, v19, v18
	v_div_scale_f32 v19, vcc, v20, v12, v20
	v_mul_f32_e32 v21, v19, v18
	v_fma_f32 v22, -v16, v21, v19
	v_fmac_f32_e32 v21, v22, v18
	v_fma_f32 v16, -v16, v21, v19
	v_div_fmas_f32 v16, v16, v18, v21
	v_div_fixup_f32 v12, v16, v12, v20
	v_lshlrev_b32_e32 v16, 16, v17
	v_and_b32_e32 v17, 0xffff0000, v17
	v_pk_mul_f32 v[8:9], v[8:9], v[12:13]
	v_mul_f32_e32 v12, 0xbfb8aa3b, v16
	v_mul_f32_e32 v13, 0xbfb8aa3b, v17
	v_exp_f32_e32 v12, v12
	v_exp_f32_e32 v13, v13
	v_cvt_pk_bf16_f32 v8, v8, v9
	v_pk_add_f32 v[12:13], v[12:13], 1.0 op_sel_hi:[1,0]
	s_nop 0
	v_div_scale_f32 v14, s[2:3], v13, v13, v17
	v_rcp_f32_e32 v15, v14
	s_nop 0
	v_fma_f32 v18, -v14, v15, 1.0
	v_fmac_f32_e32 v15, v18, v15
	v_div_scale_f32 v18, vcc, v17, v13, v17
	v_mul_f32_e32 v19, v18, v15
	v_fma_f32 v20, -v14, v19, v18
	v_fmac_f32_e32 v19, v20, v15
	v_fma_f32 v14, -v14, v19, v18
	v_div_fmas_f32 v14, v14, v15, v19
	v_div_fixup_f32 v13, v14, v13, v17
	v_div_scale_f32 v14, s[2:3], v12, v12, v16
	v_rcp_f32_e32 v15, v14
	s_nop 0
	v_fma_f32 v17, -v14, v15, 1.0
	v_fmac_f32_e32 v15, v17, v15
	v_div_scale_f32 v17, vcc, v16, v12, v16
	v_mul_f32_e32 v18, v17, v15
	v_fma_f32 v19, -v14, v18, v17
	v_fmac_f32_e32 v18, v19, v15
	v_fma_f32 v14, -v14, v18, v17
	v_div_fmas_f32 v14, v14, v15, v18
	v_div_fixup_f32 v12, v14, v12, v16
	v_pk_mul_f32 v[10:11], v[10:11], v[12:13]
	s_nop 0
	v_cvt_pk_bf16_f32 v9, v10, v11
	global_store_dwordx2 v[144:145], v[8:9], off offset:208
	global_load_dwordx2 v[12:13], v[70:71], off offset:2272
	s_nop 0
	global_load_dwordx4 v[8:11], v73, s[38:39] offset:448
	s_waitcnt vmcnt(1)
	v_lshlrev_b32_e32 v16, 16, v12
	v_and_b32_e32 v12, 0xffff0000, v12
	v_mul_f32_e32 v14, 0xbfb8aa3b, v16
	s_waitcnt vmcnt(0)
	v_pk_mul_f32 v[6:7], v[6:7], v[8:9]
	v_mul_f32_e32 v8, 0xbfb8aa3b, v12
	v_exp_f32_e32 v14, v14
	v_exp_f32_e32 v15, v8
	v_pk_mul_f32 v[4:5], v[4:5], v[10:11]
	v_pk_add_f32 v[8:9], v[14:15], 1.0 op_sel_hi:[1,0]
	s_nop 0
	v_div_scale_f32 v14, s[2:3], v9, v9, v12
	v_rcp_f32_e32 v15, v14
	s_nop 0
	v_fma_f32 v17, -v14, v15, 1.0
	v_fmac_f32_e32 v15, v17, v15
	v_div_scale_f32 v17, vcc, v12, v9, v12
	v_mul_f32_e32 v18, v17, v15
	v_fma_f32 v19, -v14, v18, v17
	v_fmac_f32_e32 v18, v19, v15
	v_fma_f32 v14, -v14, v18, v17
	v_div_fmas_f32 v14, v14, v15, v18
	v_div_fixup_f32 v9, v14, v9, v12
	v_div_scale_f32 v12, s[2:3], v8, v8, v16
	v_rcp_f32_e32 v14, v12
	s_nop 0
	v_fma_f32 v15, -v12, v14, 1.0
	v_fmac_f32_e32 v14, v15, v14
	v_div_scale_f32 v15, vcc, v16, v8, v16
	v_mul_f32_e32 v17, v15, v14
	v_fma_f32 v18, -v12, v17, v15
	v_fmac_f32_e32 v17, v18, v14
	v_fma_f32 v12, -v12, v17, v15
	v_div_fmas_f32 v12, v12, v14, v17
	v_div_fixup_f32 v8, v12, v8, v16
	v_lshlrev_b32_e32 v12, 16, v13
	v_and_b32_e32 v13, 0xffff0000, v13
	v_pk_mul_f32 v[6:7], v[6:7], v[8:9]
	v_mul_f32_e32 v8, 0xbfb8aa3b, v12
	v_mul_f32_e32 v9, 0xbfb8aa3b, v13
	v_exp_f32_e32 v8, v8
	v_exp_f32_e32 v9, v9
	v_cvt_pk_bf16_f32 v6, v6, v7
	v_pk_add_f32 v[8:9], v[8:9], 1.0 op_sel_hi:[1,0]
	s_nop 0
	v_div_scale_f32 v10, s[2:3], v9, v9, v13
	v_rcp_f32_e32 v11, v10
	s_nop 0
	v_fma_f32 v14, -v10, v11, 1.0
	v_fmac_f32_e32 v11, v14, v11
	v_div_scale_f32 v14, vcc, v13, v9, v13
	v_mul_f32_e32 v15, v14, v11
	v_fma_f32 v16, -v10, v15, v14
	v_fmac_f32_e32 v15, v16, v11
	v_fma_f32 v10, -v10, v15, v14
	v_div_fmas_f32 v10, v10, v11, v15
	v_div_fixup_f32 v9, v10, v9, v13
	v_div_scale_f32 v10, s[2:3], v8, v8, v12
	v_rcp_f32_e32 v11, v10
	s_nop 0
	v_fma_f32 v13, -v10, v11, 1.0
	v_fmac_f32_e32 v11, v13, v11
	v_div_scale_f32 v13, vcc, v12, v8, v12
	v_mul_f32_e32 v14, v13, v11
	v_fma_f32 v15, -v10, v14, v13
	v_fmac_f32_e32 v14, v15, v11
	v_fma_f32 v10, -v10, v14, v13
	v_div_fmas_f32 v10, v10, v11, v14
	v_div_fixup_f32 v8, v10, v8, v12
	v_pk_mul_f32 v[4:5], v[4:5], v[8:9]
	v_pk_mul_f32 v[12:13], v[68:69], v[2:3] op_sel_hi:[1,0]
	v_cvt_pk_bf16_f32 v7, v4, v5
	global_store_dwordx2 v[144:145], v[6:7], off offset:224
	global_load_dwordx2 v[8:9], v[70:71], off offset:2288
	s_waitcnt vmcnt(0)
	v_lshlrev_b32_e32 v14, 16, v8
	global_load_dwordx4 v[4:7], v73, s[38:39] offset:480
	v_and_b32_e32 v8, 0xffff0000, v8
	v_mul_f32_e32 v10, 0xbfb8aa3b, v14
	v_mul_f32_e32 v11, 0xbfb8aa3b, v8
	v_exp_f32_e32 v10, v10
	v_exp_f32_e32 v11, v11
	s_waitcnt vmcnt(0)
	v_pk_mul_f32 v[4:5], v[12:13], v[4:5]
	v_pk_add_f32 v[10:11], v[10:11], 1.0 op_sel_hi:[1,0]
	v_pk_mul_f32 v[0:1], v[0:1], v[6:7]
	v_div_scale_f32 v12, s[2:3], v11, v11, v8
	v_rcp_f32_e32 v13, v12
	s_nop 0
	v_fma_f32 v15, -v12, v13, 1.0
	v_fmac_f32_e32 v13, v15, v13
	v_div_scale_f32 v15, vcc, v8, v11, v8
	v_mul_f32_e32 v16, v15, v13
	v_fma_f32 v17, -v12, v16, v15
	v_fmac_f32_e32 v16, v17, v13
	v_fma_f32 v12, -v12, v16, v15
	v_div_fmas_f32 v12, v12, v13, v16
	v_div_fixup_f32 v11, v12, v11, v8
	v_div_scale_f32 v8, s[2:3], v10, v10, v14
	v_rcp_f32_e32 v12, v8
	s_nop 0
	v_fma_f32 v13, -v8, v12, 1.0
	v_fmac_f32_e32 v12, v13, v12
	v_div_scale_f32 v13, vcc, v14, v10, v14
	v_mul_f32_e32 v15, v13, v12
	v_fma_f32 v16, -v8, v15, v13
	v_fmac_f32_e32 v15, v16, v12
	v_fma_f32 v8, -v8, v15, v13
	v_div_fmas_f32 v8, v8, v12, v15
	v_div_fixup_f32 v10, v8, v10, v14
	v_pk_mul_f32 v[4:5], v[4:5], v[10:11]
	v_lshlrev_b32_e32 v10, 16, v9
	v_and_b32_e32 v11, 0xffff0000, v9
	v_mul_f32_e32 v8, 0xbfb8aa3b, v10
	v_mul_f32_e32 v2, 0xbfb8aa3b, v11
	v_exp_f32_e32 v8, v8
	v_exp_f32_e32 v9, v2
	v_cvt_pk_bf16_f32 v4, v4, v5
	v_pk_add_f32 v[6:7], v[8:9], 1.0 op_sel_hi:[1,0]
	s_nop 0
	v_div_scale_f32 v2, s[2:3], v7, v7, v11
	v_rcp_f32_e32 v8, v2
	s_nop 0
	v_fma_f32 v9, -v2, v8, 1.0
	v_fmac_f32_e32 v8, v9, v8
	v_div_scale_f32 v9, vcc, v11, v7, v11
	v_mul_f32_e32 v12, v9, v8
	v_fma_f32 v13, -v2, v12, v9
	v_fmac_f32_e32 v12, v13, v8
	v_fma_f32 v2, -v2, v12, v9
	v_div_fmas_f32 v2, v2, v8, v12
	v_div_fixup_f32 v7, v2, v7, v11
	v_div_scale_f32 v2, s[2:3], v6, v6, v10
	v_rcp_f32_e32 v8, v2
	s_mov_b64 s[2:3], 0
	v_fma_f32 v9, -v2, v8, 1.0
	v_fmac_f32_e32 v8, v9, v8
	v_div_scale_f32 v9, vcc, v10, v6, v10
	v_mul_f32_e32 v11, v9, v8
	v_fma_f32 v12, -v2, v11, v9
	v_fmac_f32_e32 v11, v12, v8
	v_fma_f32 v2, -v2, v11, v9
	v_div_fmas_f32 v2, v2, v8, v11
	v_div_fixup_f32 v6, v2, v6, v10
	v_pk_mul_f32 v[0:1], v[0:1], v[6:7]
	s_nop 0
	v_cvt_pk_bf16_f32 v5, v0, v1
	global_store_dwordx2 v[144:145], v[4:5], off offset:240
